# prep phase: gate|up bias GEMV moved before the ticket loop (dynamic balancing absorbs it), workgroups without a bias item skip its LDS staging (on top of win1 config)
# speedup vs baseline: 1.0147x; 1.0147x over previous
.LBB0_394:
	s_cmpk_ge_i32 s90, 0x160
	s_cbranch_scc1 prep_items_l0
	s_mov_b64 s[98:99], s[14:15]
	s_branch .LBB0_424
prep_items_l0:
	s_add_u32 s6, s34, 0x1c4000
	s_addc_u32 s7, s35, 0
	s_add_u32 s8, s34, 0x1c2000
	s_addc_u32 s9, s35, 0
	s_add_u32 s10, s34, 0x1c6000
	s_addc_u32 s11, s35, 0
	s_add_u32 s70, s34, 0xda000
	s_addc_u32 s71, s35, 0
	s_add_i32 s4, 0, 0x20180
	s_mov_b32 s73, 0
	v_mov_b32_e32 v123, 0
	v_mov_b32_e32 v1, s4
	s_movk_i32 s5, 0x47f
	s_movk_i32 s19, 0x90
	s_movk_i32 s22, 0x3800
	s_movk_i32 s23, 0xc00
	s_movk_i32 s27, 0x800
	s_mov_b32 s33, 0xffff0000
	s_movk_i32 s44, 0x7fff
	v_mov_b32_e32 v127, 0x358637bd
	s_mov_b32 s45, 0xf800000
	v_mov_b32_e32 v129, 0x260
	s_movk_i32 s48, 0x110
	s_branch .LBB0_397

.LBB0_424:
	v_mov_b32_e32 v1, v0
	s_mov_b32 s1, 0x38e38e39
	v_lshlrev_b32_e32 v2, 2, v1
	v_ashrrev_i32_e32 v77, 8, v1
	v_and_b32_e32 v81, 0x3fc, v2
	v_mul_hi_i32 v2, v77, s1
	v_lshrrev_b32_e32 v3, 31, v2
	v_ashrrev_i32_e32 v2, 1, v2
	v_add_u32_e32 v83, v2, v3
	v_lshl_add_u32 v2, v83, 3, v83
	v_readlane_b32 s6, v250, 10
	v_sub_u32_e32 v76, v77, v2
	v_ashrrev_i32_e32 v2, 1, v83
	v_readlane_b32 s7, v250, 11
	v_lshl_add_u32 v2, v2, 3, v2
	s_movk_i32 s5, 0x6000
	s_waitcnt vmcnt(8)
	v_mov_b64_e32 v[62:63], s[6:7]
	v_mad_i64_i32 v[2:3], s[6:7], v2, s5, v[62:63]
	s_movk_i32 s6, 0x1800
	s_nop 0
	v_mul_lo_u32 v4, v76, s6
	v_ashrrev_i32_e32 v5, 31, v4
	v_lshl_add_u64 v[2:3], v[4:5], 2, v[2:3]
	v_bfe_i32 v4, v83, 0, 1
	v_and_b32_e32 v74, 0x3000, v4
	v_add_u32_e32 v4, 0x200, v1
	v_ashrrev_i32_e32 v79, 8, v4
	v_mul_hi_i32 v4, v79, s1
	v_lshrrev_b32_e32 v5, 31, v4
	v_ashrrev_i32_e32 v4, 1, v4
	v_add_u32_e32 v85, v4, v5
	v_lshl_add_u32 v4, v85, 3, v85
	v_sub_u32_e32 v78, v79, v4
	v_ashrrev_i32_e32 v4, 1, v85
	v_lshl_add_u32 v4, v4, 3, v4
	v_mul_lo_u32 v6, v78, s6
	v_mad_i64_i32 v[4:5], s[8:9], v4, s5, v[62:63]
	v_ashrrev_i32_e32 v7, 31, v6
	v_mov_b32_e32 v75, 0
	v_lshl_add_u64 v[4:5], v[6:7], 2, v[4:5]
	v_bfe_i32 v6, v85, 0, 1
	v_and_b32_e32 v6, 0x3000, v6
	v_mov_b32_e32 v7, v75
	v_lshl_add_u64 v[4:5], v[4:5], 0, v[6:7]
	v_add_u32_e32 v6, 0x400, v1
	v_ashrrev_i32_e32 v6, 8, v6
	v_mul_hi_i32 v7, v6, s1
	v_lshrrev_b32_e32 v8, 31, v7
	v_ashrrev_i32_e32 v7, 1, v7
	v_add_u32_e32 v87, v7, v8
	v_lshl_add_u32 v7, v87, 3, v87
	v_sub_u32_e32 v80, v6, v7
	v_ashrrev_i32_e32 v6, 1, v87
	v_lshl_add_u32 v6, v6, 3, v6
	v_mul_lo_u32 v8, v80, s6
	v_mad_i64_i32 v[6:7], s[8:9], v6, s5, v[62:63]
	v_ashrrev_i32_e32 v9, 31, v8
	v_lshl_add_u64 v[6:7], v[8:9], 2, v[6:7]
	v_bfe_i32 v8, v87, 0, 1
	v_and_b32_e32 v8, 0x3000, v8
	v_mov_b32_e32 v9, v75
	v_lshl_add_u64 v[6:7], v[6:7], 0, v[8:9]
	v_add_u32_e32 v8, 0x600, v1
	v_ashrrev_i32_e32 v8, 8, v8
	v_mul_hi_i32 v9, v8, s1
	v_lshrrev_b32_e32 v10, 31, v9
	v_ashrrev_i32_e32 v9, 1, v9
	v_add_u32_e32 v89, v9, v10
	v_lshl_add_u32 v9, v89, 3, v89
	v_sub_u32_e32 v82, v8, v9
	v_ashrrev_i32_e32 v8, 1, v89
	v_lshl_add_u32 v8, v8, 3, v8
	v_mul_lo_u32 v10, v82, s6
	v_mad_i64_i32 v[8:9], s[8:9], v8, s5, v[62:63]
	v_ashrrev_i32_e32 v11, 31, v10
	v_lshl_add_u64 v[8:9], v[10:11], 2, v[8:9]
	v_bfe_i32 v10, v89, 0, 1
	v_and_b32_e32 v10, 0x3000, v10
	v_mov_b32_e32 v11, v75
	v_lshl_add_u64 v[8:9], v[8:9], 0, v[10:11]
	v_add_u32_e32 v10, 0x800, v1
	v_ashrrev_i32_e32 v10, 8, v10
	v_mul_hi_i32 v11, v10, s1
	v_lshrrev_b32_e32 v12, 31, v11
	v_ashrrev_i32_e32 v11, 1, v11
	v_add_u32_e32 v91, v11, v12
	v_lshl_add_u32 v11, v91, 3, v91
	v_sub_u32_e32 v84, v10, v11
	v_ashrrev_i32_e32 v10, 1, v91
	v_lshl_add_u32 v10, v10, 3, v10
	v_mul_lo_u32 v12, v84, s6
	v_mad_i64_i32 v[10:11], s[8:9], v10, s5, v[62:63]
	v_ashrrev_i32_e32 v13, 31, v12
	v_lshl_add_u64 v[10:11], v[12:13], 2, v[10:11]
	v_bfe_i32 v12, v91, 0, 1
	v_and_b32_e32 v12, 0x3000, v12
	v_mov_b32_e32 v13, v75
	v_lshl_add_u64 v[10:11], v[10:11], 0, v[12:13]
	v_add_u32_e32 v12, 0xa00, v1
	v_ashrrev_i32_e32 v12, 8, v12
	v_mul_hi_i32 v13, v12, s1
	s_waitcnt vmcnt(3)
	v_lshrrev_b32_e32 v22, 31, v13
	v_ashrrev_i32_e32 v13, 1, v13
	v_add_u32_e32 v93, v13, v22
	v_lshl_add_u32 v13, v93, 3, v93
	v_sub_u32_e32 v86, v12, v13
	v_ashrrev_i32_e32 v12, 1, v93
	v_lshl_add_u32 v12, v12, 3, v12
	v_mul_lo_u32 v22, v86, s6
	v_mad_i64_i32 v[12:13], s[8:9], v12, s5, v[62:63]
	v_ashrrev_i32_e32 v23, 31, v22
	v_lshl_add_u64 v[12:13], v[22:23], 2, v[12:13]
	v_bfe_i32 v22, v93, 0, 1
	v_and_b32_e32 v22, 0x3000, v22
	v_mov_b32_e32 v23, v75
	v_lshl_add_u64 v[12:13], v[12:13], 0, v[22:23]
	v_add_u32_e32 v22, 0xc00, v1
	v_ashrrev_i32_e32 v22, 8, v22
	v_mul_hi_i32 v23, v22, s1
	v_lshrrev_b32_e32 v24, 31, v23
	v_ashrrev_i32_e32 v23, 1, v23
	v_add_u32_e32 v95, v23, v24
	v_lshl_add_u32 v23, v95, 3, v95
	v_sub_u32_e32 v88, v22, v23
	v_ashrrev_i32_e32 v22, 1, v95
	v_lshl_add_u32 v22, v22, 3, v22
	v_mul_lo_u32 v24, v88, s6
	v_mad_i64_i32 v[22:23], s[8:9], v22, s5, v[62:63]
	v_ashrrev_i32_e32 v25, 31, v24
	v_lshl_add_u64 v[22:23], v[24:25], 2, v[22:23]
	v_bfe_i32 v24, v95, 0, 1
	v_and_b32_e32 v24, 0x3000, v24
	v_mov_b32_e32 v25, v75
	v_lshl_add_u64 v[22:23], v[22:23], 0, v[24:25]
	v_add_u32_e32 v24, 0xe00, v1
	v_ashrrev_i32_e32 v24, 8, v24
	v_mul_hi_i32 v25, v24, s1
	s_waitcnt vmcnt(1)
	v_lshrrev_b32_e32 v30, 31, v25
	v_ashrrev_i32_e32 v25, 1, v25
	v_add_u32_e32 v97, v25, v30
	v_lshl_add_u32 v25, v97, 3, v97
	v_sub_u32_e32 v90, v24, v25
	v_ashrrev_i32_e32 v24, 1, v97
	v_lshl_add_u32 v24, v24, 3, v24
	v_mul_lo_u32 v30, v90, s6
	v_mad_i64_i32 v[24:25], s[8:9], v24, s5, v[62:63]
	v_ashrrev_i32_e32 v31, 31, v30
	v_lshl_add_u64 v[24:25], v[30:31], 2, v[24:25]
	v_bfe_i32 v30, v97, 0, 1
	v_and_b32_e32 v30, 0x3000, v30
	v_mov_b32_e32 v31, v75
	v_lshl_add_u64 v[24:25], v[24:25], 0, v[30:31]
	v_add_u32_e32 v30, 0x1000, v1
	v_ashrrev_i32_e32 v30, 8, v30
	v_mul_hi_i32 v31, v30, s1
	v_lshrrev_b32_e32 v32, 31, v31
	v_ashrrev_i32_e32 v31, 1, v31
	v_add_u32_e32 v99, v31, v32
	v_lshl_add_u32 v31, v99, 3, v99
	v_sub_u32_e32 v92, v30, v31
	v_ashrrev_i32_e32 v30, 1, v99
	v_lshl_add_u32 v30, v30, 3, v30
	v_mul_lo_u32 v32, v92, s6
	v_mad_i64_i32 v[30:31], s[8:9], v30, s5, v[62:63]
	v_ashrrev_i32_e32 v33, 31, v32
	v_lshl_add_u64 v[30:31], v[32:33], 2, v[30:31]
	v_bfe_i32 v32, v99, 0, 1
	v_and_b32_e32 v32, 0x3000, v32
	v_mov_b32_e32 v33, v75
	v_lshl_add_u64 v[30:31], v[30:31], 0, v[32:33]
	v_add_u32_e32 v32, 0x1200, v1
	v_ashrrev_i32_e32 v32, 8, v32
	v_mul_hi_i32 v33, v32, s1
	v_lshrrev_b32_e32 v38, 31, v33
	v_ashrrev_i32_e32 v33, 1, v33
	v_add_u32_e32 v101, v33, v38
	v_lshl_add_u32 v33, v101, 3, v101
	v_sub_u32_e32 v94, v32, v33
	v_ashrrev_i32_e32 v32, 1, v101
	v_lshl_add_u32 v32, v32, 3, v32
	v_mul_lo_u32 v38, v94, s6
	v_mad_i64_i32 v[32:33], s[8:9], v32, s5, v[62:63]
	v_ashrrev_i32_e32 v39, 31, v38
	v_lshl_add_u64 v[32:33], v[38:39], 2, v[32:33]
	v_bfe_i32 v38, v101, 0, 1
	v_and_b32_e32 v38, 0x3000, v38
	v_mov_b32_e32 v39, v75
	v_lshl_add_u64 v[32:33], v[32:33], 0, v[38:39]
	v_add_u32_e32 v38, 0x1400, v1
	v_ashrrev_i32_e32 v38, 8, v38
	v_mul_hi_i32 v39, v38, s1
	v_lshrrev_b32_e32 v40, 31, v39
	v_ashrrev_i32_e32 v39, 1, v39
	v_add_u32_e32 v103, v39, v40
	v_lshl_add_u32 v39, v103, 3, v103
	v_sub_u32_e32 v96, v38, v39
	v_ashrrev_i32_e32 v38, 1, v103
	v_lshl_add_u32 v38, v38, 3, v38
	v_mul_lo_u32 v40, v96, s6
	v_mad_i64_i32 v[38:39], s[8:9], v38, s5, v[62:63]
	v_ashrrev_i32_e32 v41, 31, v40
	v_lshl_add_u64 v[2:3], v[2:3], 0, v[74:75]
	v_lshlrev_b32_e32 v74, 2, v81
	v_lshl_add_u64 v[38:39], v[40:41], 2, v[38:39]
	v_bfe_i32 v40, v103, 0, 1
	v_lshl_add_u64 v[2:3], v[2:3], 0, v[74:75]
	v_lshl_add_u64 v[4:5], v[4:5], 0, v[74:75]
	v_and_b32_e32 v40, 0x3000, v40
	v_mov_b32_e32 v41, v75
	global_load_dwordx4 v[14:17], v[2:3], off
	s_nop 0
	global_load_dwordx4 v[2:5], v[4:5], off
	v_lshl_add_u64 v[38:39], v[38:39], 0, v[40:41]
	v_add_u32_e32 v40, 0x1600, v1
	v_ashrrev_i32_e32 v40, 8, v40
	v_mul_hi_i32 v41, v40, s1
	v_lshrrev_b32_e32 v46, 31, v41
	v_ashrrev_i32_e32 v41, 1, v41
	v_add_u32_e32 v105, v41, v46
	v_lshl_add_u32 v41, v105, 3, v105
	v_sub_u32_e32 v98, v40, v41
	v_ashrrev_i32_e32 v40, 1, v105
	v_lshl_add_u32 v40, v40, 3, v40
	v_mul_lo_u32 v46, v98, s6
	v_mad_i64_i32 v[40:41], s[8:9], v40, s5, v[62:63]
	v_ashrrev_i32_e32 v47, 31, v46
	v_lshl_add_u64 v[40:41], v[46:47], 2, v[40:41]
	v_bfe_i32 v46, v105, 0, 1
	v_and_b32_e32 v46, 0x3000, v46
	v_mov_b32_e32 v47, v75
	v_lshl_add_u64 v[40:41], v[40:41], 0, v[46:47]
	v_add_u32_e32 v46, 0x1800, v1
	v_ashrrev_i32_e32 v46, 8, v46
	v_mul_hi_i32 v47, v46, s1
	v_lshrrev_b32_e32 v48, 31, v47
	v_ashrrev_i32_e32 v47, 1, v47
	v_add_u32_e32 v107, v47, v48
	v_lshl_add_u32 v47, v107, 3, v107
	v_sub_u32_e32 v100, v46, v47
	v_ashrrev_i32_e32 v46, 1, v107
	v_lshl_add_u64 v[6:7], v[6:7], 0, v[74:75]
	v_lshl_add_u64 v[8:9], v[8:9], 0, v[74:75]
	v_lshl_add_u32 v46, v46, 3, v46
	v_mul_lo_u32 v48, v100, s6
	global_load_dwordx4 v[18:21], v[6:7], off
	s_nop 0
	global_load_dwordx4 v[6:9], v[8:9], off
	v_mad_i64_i32 v[46:47], s[8:9], v46, s5, v[62:63]
	v_ashrrev_i32_e32 v49, 31, v48
	v_lshl_add_u64 v[46:47], v[48:49], 2, v[46:47]
	v_bfe_i32 v48, v107, 0, 1
	v_and_b32_e32 v48, 0x3000, v48
	v_mov_b32_e32 v49, v75
	v_lshl_add_u64 v[46:47], v[46:47], 0, v[48:49]
	v_add_u32_e32 v48, 0x1a00, v1
	v_ashrrev_i32_e32 v48, 8, v48
	v_mul_hi_i32 v49, v48, s1
	v_lshrrev_b32_e32 v54, 31, v49
	v_ashrrev_i32_e32 v49, 1, v49
	v_add_u32_e32 v109, v49, v54
	v_lshl_add_u32 v49, v109, 3, v109
	v_sub_u32_e32 v102, v48, v49
	v_ashrrev_i32_e32 v48, 1, v109
	v_lshl_add_u32 v48, v48, 3, v48
	v_mul_lo_u32 v54, v102, s6
	v_mad_i64_i32 v[48:49], s[8:9], v48, s5, v[62:63]
	v_ashrrev_i32_e32 v55, 31, v54
	v_lshl_add_u64 v[48:49], v[54:55], 2, v[48:49]
	v_bfe_i32 v54, v109, 0, 1
	v_and_b32_e32 v54, 0x3000, v54
	v_mov_b32_e32 v55, v75
	v_lshl_add_u64 v[48:49], v[48:49], 0, v[54:55]
	v_add_u32_e32 v54, 0x1c00, v1
	v_ashrrev_i32_e32 v54, 8, v54
	v_mul_hi_i32 v55, v54, s1
	v_lshl_add_u64 v[10:11], v[10:11], 0, v[74:75]
	v_lshl_add_u64 v[12:13], v[12:13], 0, v[74:75]
	v_lshrrev_b32_e32 v56, 31, v55
	v_ashrrev_i32_e32 v55, 1, v55
	global_load_dwordx4 v[26:29], v[10:11], off
	s_nop 0
	global_load_dwordx4 v[10:13], v[12:13], off
	v_add_u32_e32 v111, v55, v56
	v_lshl_add_u32 v55, v111, 3, v111
	v_sub_u32_e32 v104, v54, v55
	v_ashrrev_i32_e32 v54, 1, v111
	v_lshl_add_u32 v54, v54, 3, v54
	v_mul_lo_u32 v56, v104, s6
	v_mad_i64_i32 v[54:55], s[8:9], v54, s5, v[62:63]
	v_ashrrev_i32_e32 v57, 31, v56
	v_lshl_add_u64 v[54:55], v[56:57], 2, v[54:55]
	v_bfe_i32 v56, v111, 0, 1
	v_and_b32_e32 v56, 0x3000, v56
	v_mov_b32_e32 v57, v75
	v_lshl_add_u64 v[54:55], v[54:55], 0, v[56:57]
	v_add_u32_e32 v56, 0x1e00, v1
	v_ashrrev_i32_e32 v56, 8, v56
	v_mul_hi_i32 v57, v56, s1
	v_lshrrev_b32_e32 v64, 31, v57
	v_ashrrev_i32_e32 v57, 1, v57
	v_add_u32_e32 v112, v57, v64
	v_lshl_add_u32 v57, v112, 3, v112
	v_sub_u32_e32 v106, v56, v57
	v_ashrrev_i32_e32 v56, 1, v112
	v_lshl_add_u32 v56, v56, 3, v56
	v_mul_lo_u32 v64, v106, s6
	v_mad_i64_i32 v[56:57], s[8:9], v56, s5, v[62:63]
	v_ashrrev_i32_e32 v65, 31, v64
	v_lshl_add_u64 v[56:57], v[64:65], 2, v[56:57]
	v_bfe_i32 v64, v112, 0, 1
	v_lshl_add_u64 v[22:23], v[22:23], 0, v[74:75]
	v_lshl_add_u64 v[24:25], v[24:25], 0, v[74:75]
	v_and_b32_e32 v64, 0x3000, v64
	v_mov_b32_e32 v65, v75
	global_load_dwordx4 v[34:37], v[22:23], off
	s_nop 0
	global_load_dwordx4 v[22:25], v[24:25], off
	v_lshl_add_u64 v[56:57], v[56:57], 0, v[64:65]
	v_add_u32_e32 v64, 0x2000, v1
	v_ashrrev_i32_e32 v64, 8, v64
	v_mul_hi_i32 v65, v64, s1
	v_lshrrev_b32_e32 v70, 31, v65
	v_ashrrev_i32_e32 v65, 1, v65
	v_add_u32_e32 v113, v65, v70
	v_lshl_add_u32 v65, v113, 3, v113
	v_sub_u32_e32 v108, v64, v65
	v_ashrrev_i32_e32 v64, 1, v113
	v_lshl_add_u32 v64, v64, 3, v64
	v_mul_lo_u32 v70, v108, s6
	v_mad_i64_i32 v[64:65], s[8:9], v64, s5, v[62:63]
	v_ashrrev_i32_e32 v71, 31, v70
	v_lshl_add_u64 v[64:65], v[70:71], 2, v[64:65]
	v_bfe_i32 v70, v113, 0, 1
	v_and_b32_e32 v70, 0x3000, v70
	v_mov_b32_e32 v71, v75
	v_lshl_add_u64 v[64:65], v[64:65], 0, v[70:71]
	v_add_u32_e32 v70, 0x2200, v1
	v_ashrrev_i32_e32 v70, 8, v70
	v_mul_hi_i32 v71, v70, s1
	v_lshrrev_b32_e32 v72, 31, v71
	v_ashrrev_i32_e32 v71, 1, v71
	v_add_u32_e32 v114, v71, v72
	v_lshl_add_u32 v71, v114, 3, v114
	v_lshl_add_u64 v[30:31], v[30:31], 0, v[74:75]
	v_lshl_add_u64 v[32:33], v[32:33], 0, v[74:75]
	v_sub_u32_e32 v110, v70, v71
	v_ashrrev_i32_e32 v70, 1, v114
	global_load_dwordx4 v[42:45], v[30:31], off
	s_nop 0
	global_load_dwordx4 v[30:33], v[32:33], off
	v_lshl_add_u32 v70, v70, 3, v70
	v_mad_i64_i32 v[62:63], s[8:9], v70, s5, v[62:63]
	v_mul_lo_u32 v70, v110, s6
	v_ashrrev_i32_e32 v71, 31, v70
	v_lshl_add_u64 v[62:63], v[70:71], 2, v[62:63]
	v_bfe_i32 v70, v114, 0, 1
	v_and_b32_e32 v70, 0x3000, v70
	v_mov_b32_e32 v71, v75
	v_lshl_add_u64 v[62:63], v[62:63], 0, v[70:71]
	v_lshl_add_u64 v[38:39], v[38:39], 0, v[74:75]
	v_lshl_add_u64 v[40:41], v[40:41], 0, v[74:75]
	v_lshl_add_u64 v[46:47], v[46:47], 0, v[74:75]
	v_lshl_add_u64 v[48:49], v[48:49], 0, v[74:75]
	v_lshl_add_u64 v[54:55], v[54:55], 0, v[74:75]
	v_lshl_add_u64 v[56:57], v[56:57], 0, v[74:75]
	v_lshl_add_u64 v[64:65], v[64:65], 0, v[74:75]
	v_lshl_add_u64 v[62:63], v[62:63], 0, v[74:75]
	s_waitcnt vmcnt(9)
	v_bfe_u32 v74, v14, 16, 1
	s_movk_i32 s1, 0x7fff
	v_add3_u32 v14, v14, v74, s1
	v_bfe_u32 v74, v15, 16, 1
	v_lshrrev_b32_e32 v14, 16, v14
	v_add3_u32 v15, v15, v74, s1
	s_mov_b32 s5, 0xffff0000
	v_and_or_b32 v14, v15, s5, v14
	v_bfe_u32 v15, v16, 16, 1
	v_add3_u32 v15, v16, v15, s1
	v_bfe_u32 v16, v17, 16, 1
	v_lshrrev_b32_e32 v15, 16, v15
	v_add3_u32 v16, v17, v16, s1
	v_and_or_b32 v15, v16, s5, v15
	v_mad_u64_u32 v[16:17], s[6:7], v83, 10, v[76:77]
	s_movk_i32 s6, 0x810
	s_nop 0
	v_mul_lo_u32 v16, v16, s6
	v_lshlrev_b32_e32 v17, 1, v81
	v_add3_u32 v16, 0, v16, v17
	global_load_dwordx4 v[50:53], v[38:39], off
	s_nop 0
	global_load_dwordx4 v[38:41], v[40:41], off
	s_nop 0
	global_load_dwordx4 v[58:61], v[46:47], off
	s_nop 0
	global_load_dwordx4 v[46:49], v[48:49], off
	s_nop 0
	global_load_dwordx4 v[66:69], v[54:55], off
	s_nop 0
	global_load_dwordx4 v[54:57], v[56:57], off
	s_nop 0
	global_load_dwordx4 v[70:73], v[64:65], off
	s_nop 0
	global_load_dwordx4 v[62:65], v[62:63], off
	ds_write_b64 v16, v[14:15]
	s_waitcnt vmcnt(16)
	v_bfe_u32 v14, v2, 16, 1
	v_add3_u32 v2, v2, v14, s1
	v_bfe_u32 v14, v3, 16, 1
	v_lshrrev_b32_e32 v2, 16, v2
	v_add3_u32 v3, v3, v14, s1
	v_and_or_b32 v2, v3, s5, v2
	v_bfe_u32 v3, v4, 16, 1
	v_add3_u32 v3, v4, v3, s1
	v_bfe_u32 v4, v5, 16, 1
	v_lshrrev_b32_e32 v3, 16, v3
	v_add3_u32 v4, v5, v4, s1
	v_and_or_b32 v3, v4, s5, v3
	v_mad_u64_u32 v[4:5], s[8:9], v85, 10, v[78:79]
	v_mul_lo_u32 v4, v4, s6
	v_add3_u32 v4, 0, v4, v17
	ds_write_b64 v4, v[2:3]
	s_waitcnt vmcnt(15)
	v_bfe_u32 v2, v18, 16, 1
	v_add3_u32 v2, v18, v2, s1
	v_bfe_u32 v3, v19, 16, 1
	v_lshrrev_b32_e32 v2, 16, v2
	v_add3_u32 v3, v19, v3, s1
	v_and_or_b32 v2, v3, s5, v2
	v_bfe_u32 v3, v20, 16, 1
	v_add3_u32 v3, v20, v3, s1
	v_bfe_u32 v4, v21, 16, 1
	v_lshrrev_b32_e32 v3, 16, v3
	v_add3_u32 v4, v21, v4, s1
	v_and_or_b32 v3, v4, s5, v3
	v_mad_u64_u32 v[4:5], s[8:9], v87, 10, v[80:81]
	v_mul_lo_u32 v4, v4, s6
	v_add3_u32 v4, 0, v4, v17
	ds_write_b64 v4, v[2:3]
	s_waitcnt vmcnt(14)
	v_bfe_u32 v2, v6, 16, 1
	v_add3_u32 v2, v6, v2, s1
	v_bfe_u32 v3, v7, 16, 1
	v_lshrrev_b32_e32 v2, 16, v2
	v_add3_u32 v3, v7, v3, s1
	v_and_or_b32 v2, v3, s5, v2
	v_bfe_u32 v3, v8, 16, 1
	v_add3_u32 v3, v8, v3, s1
	v_bfe_u32 v4, v9, 16, 1
	v_lshrrev_b32_e32 v3, 16, v3
	v_add3_u32 v4, v9, v4, s1
	v_and_or_b32 v3, v4, s5, v3
	v_mad_u64_u32 v[4:5], s[8:9], v89, 10, v[82:83]
	v_mul_lo_u32 v4, v4, s6
	v_add3_u32 v4, 0, v4, v17
	ds_write_b64 v4, v[2:3]
	s_waitcnt vmcnt(13)
	v_bfe_u32 v2, v26, 16, 1
	v_add3_u32 v2, v26, v2, s1
	v_bfe_u32 v3, v27, 16, 1
	v_lshrrev_b32_e32 v2, 16, v2
	v_add3_u32 v3, v27, v3, s1
	v_and_or_b32 v2, v3, s5, v2
	v_bfe_u32 v3, v28, 16, 1
	v_add3_u32 v3, v28, v3, s1
	v_bfe_u32 v4, v29, 16, 1
	v_lshrrev_b32_e32 v3, 16, v3
	v_add3_u32 v4, v29, v4, s1
	v_and_or_b32 v3, v4, s5, v3
	v_mad_u64_u32 v[4:5], s[8:9], v91, 10, v[84:85]
	v_mul_lo_u32 v4, v4, s6
	v_add3_u32 v4, 0, v4, v17
	ds_write_b64 v4, v[2:3]
	s_waitcnt vmcnt(12)
	v_bfe_u32 v2, v10, 16, 1
	v_add3_u32 v2, v10, v2, s1
	v_bfe_u32 v3, v11, 16, 1
	v_lshrrev_b32_e32 v2, 16, v2
	v_add3_u32 v3, v11, v3, s1
	v_and_or_b32 v2, v3, s5, v2
	v_bfe_u32 v3, v12, 16, 1
	v_add3_u32 v3, v12, v3, s1
	v_bfe_u32 v4, v13, 16, 1
	v_lshrrev_b32_e32 v3, 16, v3
	v_add3_u32 v4, v13, v4, s1
	v_and_or_b32 v3, v4, s5, v3
	v_mad_u64_u32 v[4:5], s[8:9], v93, 10, v[86:87]
	v_mul_lo_u32 v4, v4, s6
	v_add3_u32 v4, 0, v4, v17
	ds_write_b64 v4, v[2:3]
	s_waitcnt vmcnt(11)
	v_bfe_u32 v2, v34, 16, 1
	v_add3_u32 v2, v34, v2, s1
	v_bfe_u32 v3, v35, 16, 1
	v_lshrrev_b32_e32 v2, 16, v2
	v_add3_u32 v3, v35, v3, s1
	v_and_or_b32 v2, v3, s5, v2
	v_bfe_u32 v3, v36, 16, 1
	v_add3_u32 v3, v36, v3, s1
	v_bfe_u32 v4, v37, 16, 1
	v_lshrrev_b32_e32 v3, 16, v3
	v_add3_u32 v4, v37, v4, s1
	v_and_or_b32 v3, v4, s5, v3
	v_mad_u64_u32 v[4:5], s[8:9], v95, 10, v[88:89]
	v_mul_lo_u32 v4, v4, s6
	v_add3_u32 v4, 0, v4, v17
	ds_write_b64 v4, v[2:3]
	s_waitcnt vmcnt(10)
	v_bfe_u32 v2, v22, 16, 1
	v_add3_u32 v2, v22, v2, s1
	v_bfe_u32 v3, v23, 16, 1
	v_lshrrev_b32_e32 v2, 16, v2
	v_add3_u32 v3, v23, v3, s1
	v_and_or_b32 v2, v3, s5, v2
	v_bfe_u32 v3, v24, 16, 1
	v_add3_u32 v3, v24, v3, s1
	v_bfe_u32 v4, v25, 16, 1
	v_lshrrev_b32_e32 v3, 16, v3
	v_add3_u32 v4, v25, v4, s1
	v_and_or_b32 v3, v4, s5, v3
	v_mad_u64_u32 v[4:5], s[8:9], v97, 10, v[90:91]
	v_mul_lo_u32 v4, v4, s6
	v_add3_u32 v4, 0, v4, v17
	ds_write_b64 v4, v[2:3]
	s_waitcnt vmcnt(9)
	v_bfe_u32 v2, v42, 16, 1
	v_add3_u32 v2, v42, v2, s1
	v_bfe_u32 v3, v43, 16, 1
	v_lshrrev_b32_e32 v2, 16, v2
	v_add3_u32 v3, v43, v3, s1
	v_and_or_b32 v2, v3, s5, v2
	v_bfe_u32 v3, v44, 16, 1
	v_add3_u32 v3, v44, v3, s1
	v_bfe_u32 v4, v45, 16, 1
	v_lshrrev_b32_e32 v3, 16, v3
	v_add3_u32 v4, v45, v4, s1
	v_and_or_b32 v3, v4, s5, v3
	v_mad_u64_u32 v[4:5], s[8:9], v99, 10, v[92:93]
	v_mul_lo_u32 v4, v4, s6
	v_add3_u32 v4, 0, v4, v17
	ds_write_b64 v4, v[2:3]
	s_waitcnt vmcnt(8)
	v_bfe_u32 v2, v30, 16, 1
	v_add3_u32 v2, v30, v2, s1
	v_bfe_u32 v3, v31, 16, 1
	v_lshrrev_b32_e32 v2, 16, v2
	v_add3_u32 v3, v31, v3, s1
	v_and_or_b32 v2, v3, s5, v2
	v_bfe_u32 v3, v32, 16, 1
	v_add3_u32 v3, v32, v3, s1
	v_bfe_u32 v4, v33, 16, 1
	v_lshrrev_b32_e32 v3, 16, v3
	v_add3_u32 v4, v33, v4, s1
	v_and_or_b32 v3, v4, s5, v3
	v_mad_u64_u32 v[4:5], s[8:9], v101, 10, v[94:95]
	v_mul_lo_u32 v4, v4, s6
	v_add3_u32 v4, 0, v4, v17
	ds_write_b64 v4, v[2:3]
	s_waitcnt vmcnt(7)
	v_bfe_u32 v2, v50, 16, 1
	v_add3_u32 v2, v50, v2, s1
	v_bfe_u32 v3, v51, 16, 1
	v_lshrrev_b32_e32 v2, 16, v2
	v_add3_u32 v3, v51, v3, s1
	v_and_or_b32 v2, v3, s5, v2
	v_bfe_u32 v3, v52, 16, 1
	v_add3_u32 v3, v52, v3, s1
	v_bfe_u32 v4, v53, 16, 1
	v_lshrrev_b32_e32 v3, 16, v3
	v_add3_u32 v4, v53, v4, s1
	v_and_or_b32 v3, v4, s5, v3
	v_mad_u64_u32 v[4:5], s[8:9], v103, 10, v[96:97]
	v_mul_lo_u32 v4, v4, s6
	v_add3_u32 v4, 0, v4, v17
	ds_write_b64 v4, v[2:3]
	s_waitcnt vmcnt(6)
	v_bfe_u32 v2, v38, 16, 1
	v_add3_u32 v2, v38, v2, s1
	v_bfe_u32 v3, v39, 16, 1
	v_lshrrev_b32_e32 v2, 16, v2
	v_add3_u32 v3, v39, v3, s1
	v_and_or_b32 v2, v3, s5, v2
	v_bfe_u32 v3, v40, 16, 1
	v_add3_u32 v3, v40, v3, s1
	v_bfe_u32 v4, v41, 16, 1
	v_lshrrev_b32_e32 v3, 16, v3
	v_add3_u32 v4, v41, v4, s1
	v_and_or_b32 v3, v4, s5, v3
	v_mad_u64_u32 v[4:5], s[8:9], v105, 10, v[98:99]
	v_mul_lo_u32 v4, v4, s6
	v_add3_u32 v4, 0, v4, v17
	ds_write_b64 v4, v[2:3]
	s_waitcnt vmcnt(5)
	v_bfe_u32 v2, v58, 16, 1
	v_add3_u32 v2, v58, v2, s1
	v_bfe_u32 v3, v59, 16, 1
	v_lshrrev_b32_e32 v2, 16, v2
	v_add3_u32 v3, v59, v3, s1
	v_and_or_b32 v2, v3, s5, v2
	v_bfe_u32 v3, v60, 16, 1
	v_add3_u32 v3, v60, v3, s1
	v_bfe_u32 v4, v61, 16, 1
	v_lshrrev_b32_e32 v3, 16, v3
	v_add3_u32 v4, v61, v4, s1
	v_and_or_b32 v3, v4, s5, v3
	v_mad_u64_u32 v[4:5], s[8:9], v107, 10, v[100:101]
	v_mul_lo_u32 v4, v4, s6
	v_add3_u32 v4, 0, v4, v17
	ds_write_b64 v4, v[2:3]
	s_waitcnt vmcnt(4)
	v_bfe_u32 v2, v46, 16, 1
	v_add3_u32 v2, v46, v2, s1
	v_bfe_u32 v3, v47, 16, 1
	v_lshrrev_b32_e32 v2, 16, v2
	v_add3_u32 v3, v47, v3, s1
	v_and_or_b32 v2, v3, s5, v2
	v_bfe_u32 v3, v48, 16, 1
	v_add3_u32 v3, v48, v3, s1
	v_bfe_u32 v4, v49, 16, 1
	v_lshrrev_b32_e32 v3, 16, v3
	v_add3_u32 v4, v49, v4, s1
	v_and_or_b32 v3, v4, s5, v3
	v_mad_u64_u32 v[4:5], s[8:9], v109, 10, v[102:103]
	v_mul_lo_u32 v4, v4, s6
	v_add3_u32 v4, 0, v4, v17
	ds_write_b64 v4, v[2:3]
	s_waitcnt vmcnt(3)
	v_bfe_u32 v2, v66, 16, 1
	v_add3_u32 v2, v66, v2, s1
	v_bfe_u32 v3, v67, 16, 1
	v_lshrrev_b32_e32 v2, 16, v2
	v_add3_u32 v3, v67, v3, s1
	v_and_or_b32 v2, v3, s5, v2
	v_bfe_u32 v3, v68, 16, 1
	v_add3_u32 v3, v68, v3, s1
	v_bfe_u32 v4, v69, 16, 1
	v_lshrrev_b32_e32 v3, 16, v3
	v_add3_u32 v4, v69, v4, s1
	v_and_or_b32 v3, v4, s5, v3
	v_mad_u64_u32 v[4:5], s[8:9], v111, 10, v[104:105]
	v_mul_lo_u32 v4, v4, s6
	v_add3_u32 v4, 0, v4, v17
	ds_write_b64 v4, v[2:3]
	s_waitcnt vmcnt(2)
	v_bfe_u32 v2, v54, 16, 1
	v_add3_u32 v2, v54, v2, s1
	v_bfe_u32 v3, v55, 16, 1
	v_lshrrev_b32_e32 v2, 16, v2
	v_add3_u32 v3, v55, v3, s1
	v_and_or_b32 v2, v3, s5, v2
	v_bfe_u32 v3, v56, 16, 1
	v_add3_u32 v3, v56, v3, s1
	v_bfe_u32 v4, v57, 16, 1
	v_lshrrev_b32_e32 v3, 16, v3
	v_add3_u32 v4, v57, v4, s1
	v_and_or_b32 v3, v4, s5, v3
	v_mad_u64_u32 v[4:5], s[8:9], v112, 10, v[106:107]
	v_mul_lo_u32 v4, v4, s6
	v_add3_u32 v4, 0, v4, v17
	ds_write_b64 v4, v[2:3]
	s_waitcnt vmcnt(1)
	v_bfe_u32 v2, v70, 16, 1
	v_add3_u32 v2, v70, v2, s1
	v_bfe_u32 v3, v71, 16, 1
	v_lshrrev_b32_e32 v2, 16, v2
	v_add3_u32 v3, v71, v3, s1
	v_and_or_b32 v2, v3, s5, v2
	v_bfe_u32 v3, v72, 16, 1
	v_add3_u32 v3, v72, v3, s1
	v_bfe_u32 v4, v73, 16, 1
	v_lshrrev_b32_e32 v3, 16, v3
	v_add3_u32 v4, v73, v4, s1
	v_and_or_b32 v3, v4, s5, v3
	v_mad_u64_u32 v[4:5], s[8:9], v113, 10, v[108:109]
	v_mul_lo_u32 v4, v4, s6
	v_add3_u32 v4, 0, v4, v17
	ds_write_b64 v4, v[2:3]
	s_waitcnt vmcnt(0)
	v_bfe_u32 v2, v62, 16, 1
	v_add3_u32 v2, v62, v2, s1
	v_bfe_u32 v3, v63, 16, 1
	v_lshrrev_b32_e32 v2, 16, v2
	v_add3_u32 v3, v63, v3, s1
	v_and_or_b32 v2, v3, s5, v2
	v_bfe_u32 v3, v64, 16, 1
	v_add3_u32 v3, v64, v3, s1
	v_bfe_u32 v4, v65, 16, 1
	v_lshrrev_b32_e32 v3, 16, v3
	v_add3_u32 v4, v65, v4, s1
	v_and_or_b32 v3, v4, s5, v3
	v_mad_u64_u32 v[4:5], s[8:9], v114, 10, v[110:111]
	v_readfirstlane_b32 s0, v1
	v_mul_lo_u32 v4, v4, s6
	s_ashr_i32 s4, s0, 6
	s_mov_b32 s0, 0
	v_add3_u32 v4, 0, v4, v17
	ds_write_b64 v4, v[2:3]
	v_mul_i32_i24_e32 v2, 0x50a0, v77
	s_mov_b32 s1, s0
	v_add3_u32 v2, 0, v2, v17
	v_mov_b64_e32 v[4:5], s[0:1]
	ds_write_b64 v2, v[4:5] offset:18576
	v_mul_i32_i24_e32 v2, 0x50a0, v79
	s_add_i32 s5, s4, s90
	v_add3_u32 v2, 0, v2, v17
	s_cmpk_gt_i32 s5, 0x15f
	ds_write_b64 v2, v[4:5] offset:18576
	s_waitcnt lgkmcnt(0)
	s_barrier
	s_cbranch_scc1 bias_end_l0
	v_and_b32_e32 v4, 15, v1
	v_bfe_u32 v1, v1, 4, 2
	v_lshlrev_b32_e32 v3, 2, v1
	v_min_u32_e32 v2, 9, v4
	v_or_b32_e32 v5, 1, v3
	v_or_b32_e32 v6, 2, v3
	v_or_b32_e32 v3, 3, v3
	v_lshlrev_b32_e32 v74, 2, v4
	v_cmp_gt_u32_e64 s[8:9], 9, v3
	v_mul_u32_u24_e32 v14, 0x810, v2
	v_lshl_add_u64 v[2:3], s[34:35], 0, v[74:75]
	s_mov_b64 s[12:13], 0xbc1b000
	v_cmp_gt_u32_e64 s[6:7], 9, v6
	v_lshl_add_u64 v[6:7], v[2:3], 0, s[12:13]
	s_movk_i32 s3, 0x5800
	v_mov_b32_e32 v2, 0xb000
	v_mad_u32_u24 v10, v5, s3, s3
	v_mad_u32_u24 v12, v5, s3, v2
	v_lshlrev_b32_e32 v2, 4, v1
	s_lshl_b32 s3, s91, 7
	s_lshl_b32 s4, s4, 4
	v_cmp_ne_u32_e64 s[0:1], 3, v1
	v_mul_u32_u24_e32 v74, 0x16000, v1
	v_add3_u32 v1, v14, v2, 0
	v_mov_b32_e32 v3, v75
	s_add_i32 s3, s3, s4
	v_cmp_gt_u32_e64 s[10:11], 9, v5
	v_mul_u32_u24_e32 v8, 0x5800, v5
	v_mov_b32_e32 v9, v75
	v_mov_b32_e32 v11, v75
	v_mov_b32_e32 v13, v75
	v_add_u32_e32 v1, 0x50a0, v1
	v_lshl_add_u64 v[14:15], s[34:35], 0, v[2:3]
	v_or_b32_e32 v16, s3, v4
	s_lshl_b32 s4, s94, 7
	s_branch .LBB0_427
.LBB0_426:
	s_or_b64 exec, exec, s[14:15]
	s_add_i32 s5, s5, s18
	s_cmpk_lt_i32 s5, 0x160
	v_add_u32_e32 v16, s4, v16
	s_cbranch_scc0 bias_end_l0

bias_end_l0:
	s_barrier
	s_mov_b64 s[14:15], s[98:99]
	s_branch prep_items_l0

.LBB0_1179:
	s_cmpk_ge_i32 s90, 0x160
	s_cbranch_scc1 prep_items_l1
	s_mov_b64 s[98:99], s[10:11]
	s_mov_b64 s[100:101], s[20:21]
	v_readlane_b32 s54, v250, 10
	v_readlane_b32 s55, v250, 11
	s_branch .LBB0_1209
prep_items_l1:
	s_add_u32 s4, s34, 0x1cc000
	s_addc_u32 s5, s35, 0
	s_add_u32 s6, s34, 0x1ca000
	s_addc_u32 s7, s35, 0
	s_add_u32 s8, s34, 0x1c8000
	s_addc_u32 s9, s35, 0
	s_add_u32 s26, s34, 0x1ce000
	s_addc_u32 s27, s35, 0
	s_add_u32 s28, s34, 0xec000
	s_addc_u32 s29, s35, 0
	s_add_i32 s19, 0, 0x20180
	v_readlane_b32 s54, v250, 10
	v_readlane_b32 s56, v250, 8
	s_mov_b32 s37, 0
	v_mov_b32_e32 v123, 0
	v_mov_b32_e32 v1, s19
	s_movk_i32 s22, 0x3ff
	s_movk_i32 s23, 0xc00
	s_movk_i32 s33, 0x800
	s_mov_b32 s44, 0xffff0000
	s_movk_i32 s45, 0x7fff
	s_movk_i32 s48, 0x90
	v_mov_b32_e32 v127, 0x358637bd
	s_mov_b32 s49, 0xf800000
	v_mov_b32_e32 v129, 0x260
	s_movk_i32 s52, 0x110
	v_mov_b32_e32 v131, 0x7ff
	v_readlane_b32 s55, v250, 11
	v_readlane_b32 s57, v250, 9
	s_branch .LBB0_1182

.LBB0_1209:
	v_mov_b32_e32 v1, v0
	s_mov_b32 s1, 0x38e38e39
	v_lshlrev_b32_e32 v2, 2, v1
	v_ashrrev_i32_e32 v77, 8, v1
	v_and_b32_e32 v81, 0x3fc, v2
	v_mul_hi_i32 v2, v77, s1
	v_lshrrev_b32_e32 v3, 31, v2
	v_ashrrev_i32_e32 v2, 1, v2
	v_add_u32_e32 v83, v2, v3
	v_lshl_add_u32 v2, v83, 3, v83
	v_sub_u32_e32 v76, v77, v2
	v_ashrrev_i32_e32 v2, 1, v83
	s_movk_i32 s5, 0x1800
	v_lshl_add_u32 v2, v2, 3, v2
	s_movk_i32 s4, 0x6000
	s_waitcnt vmcnt(8)
	v_mov_b64_e32 v[62:63], s[54:55]
	v_mul_lo_u32 v4, v76, s5
	v_mad_i64_i32 v[2:3], s[6:7], v2, s4, v[62:63]
	v_ashrrev_i32_e32 v5, 31, v4
	v_lshl_add_u64 v[2:3], v[4:5], 2, v[2:3]
	v_bfe_i32 v4, v83, 0, 1
	v_and_b32_e32 v74, 0x3000, v4
	v_mov_b32_e32 v75, 0
	v_lshl_add_u64 v[2:3], v[2:3], 0, v[74:75]
	v_lshlrev_b32_e32 v74, 2, v81
	v_lshl_add_u64 v[6:7], v[2:3], 0, v[74:75]
	v_add_u32_e32 v2, 0x200, v1
	v_ashrrev_i32_e32 v79, 8, v2
	v_mul_hi_i32 v2, v79, s1
	v_lshrrev_b32_e32 v3, 31, v2
	v_ashrrev_i32_e32 v2, 1, v2
	v_add_u32_e32 v85, v2, v3
	v_lshl_add_u32 v2, v85, 3, v85
	v_sub_u32_e32 v78, v79, v2
	v_ashrrev_i32_e32 v2, 1, v85
	v_lshl_add_u32 v2, v2, 3, v2
	v_mul_lo_u32 v4, v78, s5
	v_mad_i64_i32 v[2:3], s[6:7], v2, s4, v[62:63]
	v_ashrrev_i32_e32 v5, 31, v4
	v_lshl_add_u64 v[2:3], v[4:5], 2, v[2:3]
	v_bfe_i32 v4, v85, 0, 1
	v_and_b32_e32 v4, 0x3000, v4
	v_mov_b32_e32 v5, v75
	v_lshl_add_u64 v[2:3], v[2:3], 0, v[4:5]
	v_lshl_add_u64 v[8:9], v[2:3], 0, v[74:75]
	global_load_dwordx4 v[10:13], v[6:7], off
	global_load_dwordx4 v[2:5], v[8:9], off
	v_add_u32_e32 v6, 0x400, v1
	v_ashrrev_i32_e32 v6, 8, v6
	v_mul_hi_i32 v7, v6, s1
	v_lshrrev_b32_e32 v8, 31, v7
	v_ashrrev_i32_e32 v7, 1, v7
	v_add_u32_e32 v87, v7, v8
	v_lshl_add_u32 v7, v87, 3, v87
	v_sub_u32_e32 v80, v6, v7
	v_ashrrev_i32_e32 v6, 1, v87
	v_lshl_add_u32 v6, v6, 3, v6
	v_mul_lo_u32 v8, v80, s5
	v_mad_i64_i32 v[6:7], s[6:7], v6, s4, v[62:63]
	v_ashrrev_i32_e32 v9, 31, v8
	v_lshl_add_u64 v[6:7], v[8:9], 2, v[6:7]
	v_bfe_i32 v8, v87, 0, 1
	v_and_b32_e32 v8, 0x3000, v8
	v_mov_b32_e32 v9, v75
	v_lshl_add_u64 v[6:7], v[6:7], 0, v[8:9]
	v_lshl_add_u64 v[14:15], v[6:7], 0, v[74:75]
	v_add_u32_e32 v6, 0x600, v1
	v_ashrrev_i32_e32 v6, 8, v6
	v_mul_hi_i32 v7, v6, s1
	v_lshrrev_b32_e32 v8, 31, v7
	v_ashrrev_i32_e32 v7, 1, v7
	v_add_u32_e32 v89, v7, v8
	v_lshl_add_u32 v7, v89, 3, v89
	v_sub_u32_e32 v82, v6, v7
	v_ashrrev_i32_e32 v6, 1, v89
	v_lshl_add_u32 v6, v6, 3, v6
	v_mul_lo_u32 v8, v82, s5
	v_mad_i64_i32 v[6:7], s[6:7], v6, s4, v[62:63]
	v_ashrrev_i32_e32 v9, 31, v8
	v_lshl_add_u64 v[6:7], v[8:9], 2, v[6:7]
	v_bfe_i32 v8, v89, 0, 1
	v_and_b32_e32 v8, 0x3000, v8
	v_mov_b32_e32 v9, v75
	v_lshl_add_u64 v[6:7], v[6:7], 0, v[8:9]
	v_lshl_add_u64 v[16:17], v[6:7], 0, v[74:75]
	global_load_dwordx4 v[18:21], v[14:15], off
	global_load_dwordx4 v[6:9], v[16:17], off
	v_add_u32_e32 v14, 0x800, v1
	v_ashrrev_i32_e32 v14, 8, v14
	v_mul_hi_i32 v15, v14, s1
	v_lshrrev_b32_e32 v16, 31, v15
	v_ashrrev_i32_e32 v15, 1, v15
	v_add_u32_e32 v91, v15, v16
	v_lshl_add_u32 v15, v91, 3, v91
	v_sub_u32_e32 v84, v14, v15
	v_ashrrev_i32_e32 v14, 1, v91
	v_lshl_add_u32 v14, v14, 3, v14
	v_mul_lo_u32 v16, v84, s5
	v_mad_i64_i32 v[14:15], s[6:7], v14, s4, v[62:63]
	v_ashrrev_i32_e32 v17, 31, v16
	v_lshl_add_u64 v[14:15], v[16:17], 2, v[14:15]
	v_bfe_i32 v16, v91, 0, 1
	v_and_b32_e32 v16, 0x3000, v16
	v_mov_b32_e32 v17, v75
	v_lshl_add_u64 v[14:15], v[14:15], 0, v[16:17]
	s_waitcnt vmcnt(7)
	v_lshl_add_u64 v[22:23], v[14:15], 0, v[74:75]
	v_add_u32_e32 v14, 0xa00, v1
	v_ashrrev_i32_e32 v14, 8, v14
	v_mul_hi_i32 v15, v14, s1
	v_lshrrev_b32_e32 v16, 31, v15
	v_ashrrev_i32_e32 v15, 1, v15
	v_add_u32_e32 v93, v15, v16
	v_lshl_add_u32 v15, v93, 3, v93
	v_sub_u32_e32 v86, v14, v15
	v_ashrrev_i32_e32 v14, 1, v93
	v_lshl_add_u32 v14, v14, 3, v14
	v_mul_lo_u32 v16, v86, s5
	v_mad_i64_i32 v[14:15], s[6:7], v14, s4, v[62:63]
	v_ashrrev_i32_e32 v17, 31, v16
	v_lshl_add_u64 v[14:15], v[16:17], 2, v[14:15]
	v_bfe_i32 v16, v93, 0, 1
	v_and_b32_e32 v16, 0x3000, v16
	v_mov_b32_e32 v17, v75
	v_lshl_add_u64 v[14:15], v[14:15], 0, v[16:17]
	v_lshl_add_u64 v[24:25], v[14:15], 0, v[74:75]
	global_load_dwordx4 v[26:29], v[22:23], off
	global_load_dwordx4 v[14:17], v[24:25], off
	v_add_u32_e32 v22, 0xc00, v1
	v_ashrrev_i32_e32 v22, 8, v22
	v_mul_hi_i32 v23, v22, s1
	v_lshrrev_b32_e32 v24, 31, v23
	v_ashrrev_i32_e32 v23, 1, v23
	v_add_u32_e32 v95, v23, v24
	v_lshl_add_u32 v23, v95, 3, v95
	v_sub_u32_e32 v88, v22, v23
	v_ashrrev_i32_e32 v22, 1, v95
	v_lshl_add_u32 v22, v22, 3, v22
	v_mul_lo_u32 v24, v88, s5
	v_mad_i64_i32 v[22:23], s[6:7], v22, s4, v[62:63]
	v_ashrrev_i32_e32 v25, 31, v24
	v_lshl_add_u64 v[22:23], v[24:25], 2, v[22:23]
	v_bfe_i32 v24, v95, 0, 1
	v_and_b32_e32 v24, 0x3000, v24
	v_mov_b32_e32 v25, v75
	v_lshl_add_u64 v[22:23], v[22:23], 0, v[24:25]
	s_waitcnt vmcnt(7)
	v_lshl_add_u64 v[30:31], v[22:23], 0, v[74:75]
	v_add_u32_e32 v22, 0xe00, v1
	v_ashrrev_i32_e32 v22, 8, v22
	v_mul_hi_i32 v23, v22, s1
	v_lshrrev_b32_e32 v24, 31, v23
	v_ashrrev_i32_e32 v23, 1, v23
	v_add_u32_e32 v97, v23, v24
	v_lshl_add_u32 v23, v97, 3, v97
	v_sub_u32_e32 v90, v22, v23
	v_ashrrev_i32_e32 v22, 1, v97
	v_lshl_add_u32 v22, v22, 3, v22
	v_mul_lo_u32 v24, v90, s5
	v_mad_i64_i32 v[22:23], s[6:7], v22, s4, v[62:63]
	v_ashrrev_i32_e32 v25, 31, v24
	v_lshl_add_u64 v[22:23], v[24:25], 2, v[22:23]
	v_bfe_i32 v24, v97, 0, 1
	v_and_b32_e32 v24, 0x3000, v24
	v_mov_b32_e32 v25, v75
	v_lshl_add_u64 v[22:23], v[22:23], 0, v[24:25]
	v_lshl_add_u64 v[32:33], v[22:23], 0, v[74:75]
	global_load_dwordx4 v[34:37], v[30:31], off
	global_load_dwordx4 v[22:25], v[32:33], off
	v_add_u32_e32 v30, 0x1000, v1
	v_ashrrev_i32_e32 v30, 8, v30
	v_mul_hi_i32 v31, v30, s1
	v_lshrrev_b32_e32 v32, 31, v31
	v_ashrrev_i32_e32 v31, 1, v31
	v_add_u32_e32 v99, v31, v32
	v_lshl_add_u32 v31, v99, 3, v99
	v_sub_u32_e32 v92, v30, v31
	v_ashrrev_i32_e32 v30, 1, v99
	v_lshl_add_u32 v30, v30, 3, v30
	v_mul_lo_u32 v32, v92, s5
	v_mad_i64_i32 v[30:31], s[6:7], v30, s4, v[62:63]
	v_ashrrev_i32_e32 v33, 31, v32
	v_lshl_add_u64 v[30:31], v[32:33], 2, v[30:31]
	v_bfe_i32 v32, v99, 0, 1
	v_and_b32_e32 v32, 0x3000, v32
	v_mov_b32_e32 v33, v75
	v_lshl_add_u64 v[30:31], v[30:31], 0, v[32:33]
	v_lshl_add_u64 v[38:39], v[30:31], 0, v[74:75]
	v_add_u32_e32 v30, 0x1200, v1
	v_ashrrev_i32_e32 v30, 8, v30
	v_mul_hi_i32 v31, v30, s1
	v_lshrrev_b32_e32 v32, 31, v31
	v_ashrrev_i32_e32 v31, 1, v31
	v_add_u32_e32 v101, v31, v32
	v_lshl_add_u32 v31, v101, 3, v101
	v_sub_u32_e32 v94, v30, v31
	v_ashrrev_i32_e32 v30, 1, v101
	v_lshl_add_u32 v30, v30, 3, v30
	v_mul_lo_u32 v32, v94, s5
	v_mad_i64_i32 v[30:31], s[6:7], v30, s4, v[62:63]
	v_ashrrev_i32_e32 v33, 31, v32
	v_lshl_add_u64 v[30:31], v[32:33], 2, v[30:31]
	v_bfe_i32 v32, v101, 0, 1
	v_and_b32_e32 v32, 0x3000, v32
	v_mov_b32_e32 v33, v75
	v_lshl_add_u64 v[30:31], v[30:31], 0, v[32:33]
	v_lshl_add_u64 v[40:41], v[30:31], 0, v[74:75]
	global_load_dwordx4 v[42:45], v[38:39], off
	global_load_dwordx4 v[30:33], v[40:41], off
	v_add_u32_e32 v38, 0x1400, v1
	v_ashrrev_i32_e32 v38, 8, v38
	v_mul_hi_i32 v39, v38, s1
	v_lshrrev_b32_e32 v40, 31, v39
	v_ashrrev_i32_e32 v39, 1, v39
	v_add_u32_e32 v103, v39, v40
	v_lshl_add_u32 v39, v103, 3, v103
	v_sub_u32_e32 v96, v38, v39
	v_ashrrev_i32_e32 v38, 1, v103
	v_lshl_add_u32 v38, v38, 3, v38
	v_mul_lo_u32 v40, v96, s5
	v_mad_i64_i32 v[38:39], s[6:7], v38, s4, v[62:63]
	v_ashrrev_i32_e32 v41, 31, v40
	v_lshl_add_u64 v[38:39], v[40:41], 2, v[38:39]
	v_bfe_i32 v40, v103, 0, 1
	v_and_b32_e32 v40, 0x3000, v40
	v_mov_b32_e32 v41, v75
	v_lshl_add_u64 v[38:39], v[38:39], 0, v[40:41]
	v_lshl_add_u64 v[46:47], v[38:39], 0, v[74:75]
	v_add_u32_e32 v38, 0x1600, v1
	v_ashrrev_i32_e32 v38, 8, v38
	v_mul_hi_i32 v39, v38, s1
	v_lshrrev_b32_e32 v40, 31, v39
	v_ashrrev_i32_e32 v39, 1, v39
	v_add_u32_e32 v105, v39, v40
	v_lshl_add_u32 v39, v105, 3, v105
	v_sub_u32_e32 v98, v38, v39
	v_ashrrev_i32_e32 v38, 1, v105
	v_lshl_add_u32 v38, v38, 3, v38
	v_mul_lo_u32 v40, v98, s5
	v_mad_i64_i32 v[38:39], s[6:7], v38, s4, v[62:63]
	v_ashrrev_i32_e32 v41, 31, v40
	v_lshl_add_u64 v[38:39], v[40:41], 2, v[38:39]
	v_bfe_i32 v40, v105, 0, 1
	v_and_b32_e32 v40, 0x3000, v40
	v_mov_b32_e32 v41, v75
	v_lshl_add_u64 v[38:39], v[38:39], 0, v[40:41]
	v_lshl_add_u64 v[48:49], v[38:39], 0, v[74:75]
	global_load_dwordx4 v[50:53], v[46:47], off
	global_load_dwordx4 v[38:41], v[48:49], off
	v_add_u32_e32 v46, 0x1800, v1
	v_ashrrev_i32_e32 v46, 8, v46
	v_mul_hi_i32 v47, v46, s1
	v_lshrrev_b32_e32 v48, 31, v47
	v_ashrrev_i32_e32 v47, 1, v47
	v_add_u32_e32 v107, v47, v48
	v_lshl_add_u32 v47, v107, 3, v107
	v_sub_u32_e32 v100, v46, v47
	v_ashrrev_i32_e32 v46, 1, v107
	v_lshl_add_u32 v46, v46, 3, v46
	v_mul_lo_u32 v48, v100, s5
	v_mad_i64_i32 v[46:47], s[6:7], v46, s4, v[62:63]
	v_ashrrev_i32_e32 v49, 31, v48
	v_lshl_add_u64 v[46:47], v[48:49], 2, v[46:47]
	v_bfe_i32 v48, v107, 0, 1
	v_and_b32_e32 v48, 0x3000, v48
	v_mov_b32_e32 v49, v75
	v_lshl_add_u64 v[46:47], v[46:47], 0, v[48:49]
	v_lshl_add_u64 v[54:55], v[46:47], 0, v[74:75]
	v_add_u32_e32 v46, 0x1a00, v1
	v_ashrrev_i32_e32 v46, 8, v46
	v_mul_hi_i32 v47, v46, s1
	v_lshrrev_b32_e32 v48, 31, v47
	v_ashrrev_i32_e32 v47, 1, v47
	v_add_u32_e32 v109, v47, v48
	v_lshl_add_u32 v47, v109, 3, v109
	v_sub_u32_e32 v102, v46, v47
	v_ashrrev_i32_e32 v46, 1, v109
	v_lshl_add_u32 v46, v46, 3, v46
	v_mul_lo_u32 v48, v102, s5
	v_mad_i64_i32 v[46:47], s[6:7], v46, s4, v[62:63]
	v_ashrrev_i32_e32 v49, 31, v48
	v_lshl_add_u64 v[46:47], v[48:49], 2, v[46:47]
	v_bfe_i32 v48, v109, 0, 1
	v_and_b32_e32 v48, 0x3000, v48
	v_mov_b32_e32 v49, v75
	v_lshl_add_u64 v[46:47], v[46:47], 0, v[48:49]
	v_lshl_add_u64 v[56:57], v[46:47], 0, v[74:75]
	global_load_dwordx4 v[58:61], v[54:55], off
	global_load_dwordx4 v[46:49], v[56:57], off
	v_add_u32_e32 v54, 0x1c00, v1
	v_ashrrev_i32_e32 v54, 8, v54
	v_mul_hi_i32 v55, v54, s1
	v_lshrrev_b32_e32 v56, 31, v55
	v_ashrrev_i32_e32 v55, 1, v55
	v_add_u32_e32 v111, v55, v56
	v_lshl_add_u32 v55, v111, 3, v111
	v_sub_u32_e32 v104, v54, v55
	v_ashrrev_i32_e32 v54, 1, v111
	v_lshl_add_u32 v54, v54, 3, v54
	v_mul_lo_u32 v56, v104, s5
	v_mad_i64_i32 v[54:55], s[6:7], v54, s4, v[62:63]
	v_ashrrev_i32_e32 v57, 31, v56
	v_lshl_add_u64 v[54:55], v[56:57], 2, v[54:55]
	v_bfe_i32 v56, v111, 0, 1
	v_and_b32_e32 v56, 0x3000, v56
	v_mov_b32_e32 v57, v75
	v_lshl_add_u64 v[54:55], v[54:55], 0, v[56:57]
	v_lshl_add_u64 v[64:65], v[54:55], 0, v[74:75]
	v_add_u32_e32 v54, 0x1e00, v1
	v_ashrrev_i32_e32 v54, 8, v54
	v_mul_hi_i32 v55, v54, s1
	v_lshrrev_b32_e32 v56, 31, v55
	v_ashrrev_i32_e32 v55, 1, v55
	v_add_u32_e32 v116, v55, v56
	v_lshl_add_u32 v55, v116, 3, v116
	v_sub_u32_e32 v106, v54, v55
	v_ashrrev_i32_e32 v54, 1, v116
	v_lshl_add_u32 v54, v54, 3, v54
	v_mul_lo_u32 v56, v106, s5
	v_mad_i64_i32 v[54:55], s[6:7], v54, s4, v[62:63]
	v_ashrrev_i32_e32 v57, 31, v56
	v_lshl_add_u64 v[54:55], v[56:57], 2, v[54:55]
	v_bfe_i32 v56, v116, 0, 1
	v_and_b32_e32 v56, 0x3000, v56
	v_mov_b32_e32 v57, v75
	v_lshl_add_u64 v[54:55], v[54:55], 0, v[56:57]
	v_lshl_add_u64 v[70:71], v[54:55], 0, v[74:75]
	global_load_dwordx4 v[66:69], v[64:65], off
	global_load_dwordx4 v[54:57], v[70:71], off
	v_add_u32_e32 v64, 0x2000, v1
	v_ashrrev_i32_e32 v64, 8, v64
	v_mul_hi_i32 v65, v64, s1
	v_lshrrev_b32_e32 v70, 31, v65
	v_ashrrev_i32_e32 v65, 1, v65
	v_add_u32_e32 v117, v65, v70
	v_lshl_add_u32 v65, v117, 3, v117
	v_sub_u32_e32 v108, v64, v65
	v_ashrrev_i32_e32 v64, 1, v117
	v_lshl_add_u32 v64, v64, 3, v64
	v_mul_lo_u32 v70, v108, s5
	v_mad_i64_i32 v[64:65], s[6:7], v64, s4, v[62:63]
	v_ashrrev_i32_e32 v71, 31, v70
	v_lshl_add_u64 v[64:65], v[70:71], 2, v[64:65]
	v_bfe_i32 v70, v117, 0, 1
	v_and_b32_e32 v70, 0x3000, v70
	v_mov_b32_e32 v71, v75
	v_lshl_add_u64 v[64:65], v[64:65], 0, v[70:71]
	v_lshl_add_u64 v[112:113], v[64:65], 0, v[74:75]
	v_add_u32_e32 v64, 0x2200, v1
	v_ashrrev_i32_e32 v64, 8, v64
	v_mul_hi_i32 v65, v64, s1
	v_lshrrev_b32_e32 v70, 31, v65
	v_ashrrev_i32_e32 v65, 1, v65
	v_add_u32_e32 v118, v65, v70
	v_lshl_add_u32 v65, v118, 3, v118
	v_sub_u32_e32 v110, v64, v65
	v_ashrrev_i32_e32 v64, 1, v118
	v_lshl_add_u32 v64, v64, 3, v64
	v_mad_i64_i32 v[62:63], s[6:7], v64, s4, v[62:63]
	v_mul_lo_u32 v64, v110, s5
	v_ashrrev_i32_e32 v65, 31, v64
	v_lshl_add_u64 v[62:63], v[64:65], 2, v[62:63]
	v_bfe_i32 v64, v118, 0, 1
	v_and_b32_e32 v64, 0x3000, v64
	v_mov_b32_e32 v65, v75
	v_lshl_add_u64 v[62:63], v[62:63], 0, v[64:65]
	v_lshl_add_u64 v[114:115], v[62:63], 0, v[74:75]
	s_waitcnt vmcnt(15)
	v_bfe_u32 v74, v10, 16, 1
	s_movk_i32 s1, 0x7fff
	v_add3_u32 v10, v10, v74, s1
	v_bfe_u32 v74, v11, 16, 1
	v_lshrrev_b32_e32 v10, 16, v10
	v_add3_u32 v11, v11, v74, s1
	s_mov_b32 s4, 0xffff0000
	v_and_or_b32 v10, v11, s4, v10
	v_bfe_u32 v11, v12, 16, 1
	v_add3_u32 v11, v12, v11, s1
	v_bfe_u32 v12, v13, 16, 1
	v_lshrrev_b32_e32 v11, 16, v11
	v_add3_u32 v12, v13, v12, s1
	v_and_or_b32 v11, v12, s4, v11
	v_mad_u64_u32 v[12:13], s[6:7], v83, 10, v[76:77]
	s_movk_i32 s5, 0x810
	v_mul_lo_u32 v12, v12, s5
	v_lshlrev_b32_e32 v13, 1, v81
	v_add3_u32 v12, 0, v12, v13
	global_load_dwordx4 v[70:73], v[112:113], off
	global_load_dwordx4 v[62:65], v[114:115], off
	ds_write_b64 v12, v[10:11]
	s_waitcnt vmcnt(16)
	v_bfe_u32 v10, v2, 16, 1
	v_add3_u32 v2, v2, v10, s1
	v_bfe_u32 v10, v3, 16, 1
	v_lshrrev_b32_e32 v2, 16, v2
	v_add3_u32 v3, v3, v10, s1
	v_and_or_b32 v2, v3, s4, v2
	v_bfe_u32 v3, v4, 16, 1
	v_add3_u32 v3, v4, v3, s1
	v_bfe_u32 v4, v5, 16, 1
	v_lshrrev_b32_e32 v3, 16, v3
	v_add3_u32 v4, v5, v4, s1
	v_and_or_b32 v3, v4, s4, v3
	v_mad_u64_u32 v[4:5], s[6:7], v85, 10, v[78:79]
	v_mul_lo_u32 v4, v4, s5
	v_add3_u32 v4, 0, v4, v13
	ds_write_b64 v4, v[2:3]
	s_waitcnt vmcnt(15)
	v_bfe_u32 v2, v18, 16, 1
	v_add3_u32 v2, v18, v2, s1
	v_bfe_u32 v3, v19, 16, 1
	v_lshrrev_b32_e32 v2, 16, v2
	v_add3_u32 v3, v19, v3, s1
	v_and_or_b32 v2, v3, s4, v2
	v_bfe_u32 v3, v20, 16, 1
	v_add3_u32 v3, v20, v3, s1
	v_bfe_u32 v4, v21, 16, 1
	v_lshrrev_b32_e32 v3, 16, v3
	v_add3_u32 v4, v21, v4, s1
	v_and_or_b32 v3, v4, s4, v3
	v_mad_u64_u32 v[4:5], s[6:7], v87, 10, v[80:81]
	v_mul_lo_u32 v4, v4, s5
	v_add3_u32 v4, 0, v4, v13
	ds_write_b64 v4, v[2:3]
	s_waitcnt vmcnt(14)
	v_bfe_u32 v2, v6, 16, 1
	v_add3_u32 v2, v6, v2, s1
	v_bfe_u32 v3, v7, 16, 1
	v_lshrrev_b32_e32 v2, 16, v2
	v_add3_u32 v3, v7, v3, s1
	v_and_or_b32 v2, v3, s4, v2
	v_bfe_u32 v3, v8, 16, 1
	v_add3_u32 v3, v8, v3, s1
	v_bfe_u32 v4, v9, 16, 1
	v_lshrrev_b32_e32 v3, 16, v3
	v_add3_u32 v4, v9, v4, s1
	v_and_or_b32 v3, v4, s4, v3
	v_mad_u64_u32 v[4:5], s[6:7], v89, 10, v[82:83]
	v_mul_lo_u32 v4, v4, s5
	v_add3_u32 v4, 0, v4, v13
	ds_write_b64 v4, v[2:3]
	s_waitcnt vmcnt(13)
	v_bfe_u32 v2, v26, 16, 1
	v_add3_u32 v2, v26, v2, s1
	v_bfe_u32 v3, v27, 16, 1
	v_lshrrev_b32_e32 v2, 16, v2
	v_add3_u32 v3, v27, v3, s1
	v_and_or_b32 v2, v3, s4, v2
	v_bfe_u32 v3, v28, 16, 1
	v_add3_u32 v3, v28, v3, s1
	v_bfe_u32 v4, v29, 16, 1
	v_lshrrev_b32_e32 v3, 16, v3
	v_add3_u32 v4, v29, v4, s1
	v_and_or_b32 v3, v4, s4, v3
	v_mad_u64_u32 v[4:5], s[6:7], v91, 10, v[84:85]
	v_mul_lo_u32 v4, v4, s5
	v_add3_u32 v4, 0, v4, v13
	ds_write_b64 v4, v[2:3]
	s_waitcnt vmcnt(12)
	v_bfe_u32 v2, v14, 16, 1
	v_add3_u32 v2, v14, v2, s1
	v_bfe_u32 v3, v15, 16, 1
	v_lshrrev_b32_e32 v2, 16, v2
	v_add3_u32 v3, v15, v3, s1
	v_and_or_b32 v2, v3, s4, v2
	v_bfe_u32 v3, v16, 16, 1
	v_add3_u32 v3, v16, v3, s1
	v_bfe_u32 v4, v17, 16, 1
	v_lshrrev_b32_e32 v3, 16, v3
	v_add3_u32 v4, v17, v4, s1
	v_and_or_b32 v3, v4, s4, v3
	v_mad_u64_u32 v[4:5], s[6:7], v93, 10, v[86:87]
	v_mul_lo_u32 v4, v4, s5
	v_add3_u32 v4, 0, v4, v13
	ds_write_b64 v4, v[2:3]
	s_waitcnt vmcnt(11)
	v_bfe_u32 v2, v34, 16, 1
	v_add3_u32 v2, v34, v2, s1
	v_bfe_u32 v3, v35, 16, 1
	v_lshrrev_b32_e32 v2, 16, v2
	v_add3_u32 v3, v35, v3, s1
	v_and_or_b32 v2, v3, s4, v2
	v_bfe_u32 v3, v36, 16, 1
	v_add3_u32 v3, v36, v3, s1
	v_bfe_u32 v4, v37, 16, 1
	v_lshrrev_b32_e32 v3, 16, v3
	v_add3_u32 v4, v37, v4, s1
	v_and_or_b32 v3, v4, s4, v3
	v_mad_u64_u32 v[4:5], s[6:7], v95, 10, v[88:89]
	v_mul_lo_u32 v4, v4, s5
	v_add3_u32 v4, 0, v4, v13
	ds_write_b64 v4, v[2:3]
	s_waitcnt vmcnt(10)
	v_bfe_u32 v2, v22, 16, 1
	v_add3_u32 v2, v22, v2, s1
	v_bfe_u32 v3, v23, 16, 1
	v_lshrrev_b32_e32 v2, 16, v2
	v_add3_u32 v3, v23, v3, s1
	v_and_or_b32 v2, v3, s4, v2
	v_bfe_u32 v3, v24, 16, 1
	v_add3_u32 v3, v24, v3, s1
	v_bfe_u32 v4, v25, 16, 1
	v_lshrrev_b32_e32 v3, 16, v3
	v_add3_u32 v4, v25, v4, s1
	v_and_or_b32 v3, v4, s4, v3
	v_mad_u64_u32 v[4:5], s[6:7], v97, 10, v[90:91]
	v_mul_lo_u32 v4, v4, s5
	v_add3_u32 v4, 0, v4, v13
	ds_write_b64 v4, v[2:3]
	s_waitcnt vmcnt(9)
	v_bfe_u32 v2, v42, 16, 1
	v_add3_u32 v2, v42, v2, s1
	v_bfe_u32 v3, v43, 16, 1
	v_lshrrev_b32_e32 v2, 16, v2
	v_add3_u32 v3, v43, v3, s1
	v_and_or_b32 v2, v3, s4, v2
	v_bfe_u32 v3, v44, 16, 1
	v_add3_u32 v3, v44, v3, s1
	v_bfe_u32 v4, v45, 16, 1
	v_lshrrev_b32_e32 v3, 16, v3
	v_add3_u32 v4, v45, v4, s1
	v_and_or_b32 v3, v4, s4, v3
	v_mad_u64_u32 v[4:5], s[6:7], v99, 10, v[92:93]
	v_mul_lo_u32 v4, v4, s5
	v_add3_u32 v4, 0, v4, v13
	ds_write_b64 v4, v[2:3]
	s_waitcnt vmcnt(8)
	v_bfe_u32 v2, v30, 16, 1
	v_add3_u32 v2, v30, v2, s1
	v_bfe_u32 v3, v31, 16, 1
	v_lshrrev_b32_e32 v2, 16, v2
	v_add3_u32 v3, v31, v3, s1
	v_and_or_b32 v2, v3, s4, v2
	v_bfe_u32 v3, v32, 16, 1
	v_add3_u32 v3, v32, v3, s1
	v_bfe_u32 v4, v33, 16, 1
	v_lshrrev_b32_e32 v3, 16, v3
	v_add3_u32 v4, v33, v4, s1
	v_and_or_b32 v3, v4, s4, v3
	v_mad_u64_u32 v[4:5], s[6:7], v101, 10, v[94:95]
	v_mul_lo_u32 v4, v4, s5
	v_add3_u32 v4, 0, v4, v13
	ds_write_b64 v4, v[2:3]
	s_waitcnt vmcnt(7)
	v_bfe_u32 v2, v50, 16, 1
	v_add3_u32 v2, v50, v2, s1
	v_bfe_u32 v3, v51, 16, 1
	v_lshrrev_b32_e32 v2, 16, v2
	v_add3_u32 v3, v51, v3, s1
	v_and_or_b32 v2, v3, s4, v2
	v_bfe_u32 v3, v52, 16, 1
	v_add3_u32 v3, v52, v3, s1
	v_bfe_u32 v4, v53, 16, 1
	v_lshrrev_b32_e32 v3, 16, v3
	v_add3_u32 v4, v53, v4, s1
	v_and_or_b32 v3, v4, s4, v3
	v_mad_u64_u32 v[4:5], s[6:7], v103, 10, v[96:97]
	v_mul_lo_u32 v4, v4, s5
	v_add3_u32 v4, 0, v4, v13
	ds_write_b64 v4, v[2:3]
	s_waitcnt vmcnt(6)
	v_bfe_u32 v2, v38, 16, 1
	v_add3_u32 v2, v38, v2, s1
	v_bfe_u32 v3, v39, 16, 1
	v_lshrrev_b32_e32 v2, 16, v2
	v_add3_u32 v3, v39, v3, s1
	v_and_or_b32 v2, v3, s4, v2
	v_bfe_u32 v3, v40, 16, 1
	v_add3_u32 v3, v40, v3, s1
	v_bfe_u32 v4, v41, 16, 1
	v_lshrrev_b32_e32 v3, 16, v3
	v_add3_u32 v4, v41, v4, s1
	v_and_or_b32 v3, v4, s4, v3
	v_mad_u64_u32 v[4:5], s[6:7], v105, 10, v[98:99]
	v_mul_lo_u32 v4, v4, s5
	v_add3_u32 v4, 0, v4, v13
	ds_write_b64 v4, v[2:3]
	s_waitcnt vmcnt(5)
	v_bfe_u32 v2, v58, 16, 1
	v_add3_u32 v2, v58, v2, s1
	v_bfe_u32 v3, v59, 16, 1
	v_lshrrev_b32_e32 v2, 16, v2
	v_add3_u32 v3, v59, v3, s1
	v_and_or_b32 v2, v3, s4, v2
	v_bfe_u32 v3, v60, 16, 1
	v_add3_u32 v3, v60, v3, s1
	v_bfe_u32 v4, v61, 16, 1
	v_lshrrev_b32_e32 v3, 16, v3
	v_add3_u32 v4, v61, v4, s1
	v_and_or_b32 v3, v4, s4, v3
	v_mad_u64_u32 v[4:5], s[6:7], v107, 10, v[100:101]
	v_mul_lo_u32 v4, v4, s5
	v_add3_u32 v4, 0, v4, v13
	ds_write_b64 v4, v[2:3]
	s_waitcnt vmcnt(4)
	v_bfe_u32 v2, v46, 16, 1
	v_add3_u32 v2, v46, v2, s1
	v_bfe_u32 v3, v47, 16, 1
	v_lshrrev_b32_e32 v2, 16, v2
	v_add3_u32 v3, v47, v3, s1
	v_and_or_b32 v2, v3, s4, v2
	v_bfe_u32 v3, v48, 16, 1
	v_add3_u32 v3, v48, v3, s1
	v_bfe_u32 v4, v49, 16, 1
	v_lshrrev_b32_e32 v3, 16, v3
	v_add3_u32 v4, v49, v4, s1
	v_and_or_b32 v3, v4, s4, v3
	v_mad_u64_u32 v[4:5], s[6:7], v109, 10, v[102:103]
	v_mul_lo_u32 v4, v4, s5
	v_add3_u32 v4, 0, v4, v13
	ds_write_b64 v4, v[2:3]
	s_waitcnt vmcnt(3)
	v_bfe_u32 v2, v66, 16, 1
	v_add3_u32 v2, v66, v2, s1
	v_bfe_u32 v3, v67, 16, 1
	v_lshrrev_b32_e32 v2, 16, v2
	v_add3_u32 v3, v67, v3, s1
	v_and_or_b32 v2, v3, s4, v2
	v_bfe_u32 v3, v68, 16, 1
	v_add3_u32 v3, v68, v3, s1
	v_bfe_u32 v4, v69, 16, 1
	v_lshrrev_b32_e32 v3, 16, v3
	v_add3_u32 v4, v69, v4, s1
	v_and_or_b32 v3, v4, s4, v3
	v_mad_u64_u32 v[4:5], s[6:7], v111, 10, v[104:105]
	v_mul_lo_u32 v4, v4, s5
	v_add3_u32 v4, 0, v4, v13
	ds_write_b64 v4, v[2:3]
	s_waitcnt vmcnt(2)
	v_bfe_u32 v2, v54, 16, 1
	v_add3_u32 v2, v54, v2, s1
	v_bfe_u32 v3, v55, 16, 1
	v_lshrrev_b32_e32 v2, 16, v2
	v_add3_u32 v3, v55, v3, s1
	v_and_or_b32 v2, v3, s4, v2
	v_bfe_u32 v3, v56, 16, 1
	v_add3_u32 v3, v56, v3, s1
	v_bfe_u32 v4, v57, 16, 1
	v_lshrrev_b32_e32 v3, 16, v3
	v_add3_u32 v4, v57, v4, s1
	v_and_or_b32 v3, v4, s4, v3
	v_mad_u64_u32 v[4:5], s[6:7], v116, 10, v[106:107]
	v_mul_lo_u32 v4, v4, s5
	v_add3_u32 v4, 0, v4, v13
	ds_write_b64 v4, v[2:3]
	s_waitcnt vmcnt(1)
	v_bfe_u32 v2, v70, 16, 1
	v_add3_u32 v2, v70, v2, s1
	v_bfe_u32 v3, v71, 16, 1
	v_lshrrev_b32_e32 v2, 16, v2
	v_add3_u32 v3, v71, v3, s1
	v_and_or_b32 v2, v3, s4, v2
	v_bfe_u32 v3, v72, 16, 1
	v_add3_u32 v3, v72, v3, s1
	v_bfe_u32 v4, v73, 16, 1
	v_lshrrev_b32_e32 v3, 16, v3
	v_add3_u32 v4, v73, v4, s1
	v_and_or_b32 v3, v4, s4, v3
	v_mad_u64_u32 v[4:5], s[6:7], v117, 10, v[108:109]
	v_mul_lo_u32 v4, v4, s5
	v_add3_u32 v4, 0, v4, v13
	ds_write_b64 v4, v[2:3]
	s_waitcnt vmcnt(0)
	v_bfe_u32 v2, v62, 16, 1
	v_add3_u32 v2, v62, v2, s1
	v_bfe_u32 v3, v63, 16, 1
	v_lshrrev_b32_e32 v2, 16, v2
	v_add3_u32 v3, v63, v3, s1
	v_and_or_b32 v2, v3, s4, v2
	v_bfe_u32 v3, v64, 16, 1
	v_add3_u32 v3, v64, v3, s1
	v_bfe_u32 v4, v65, 16, 1
	v_lshrrev_b32_e32 v3, 16, v3
	v_add3_u32 v4, v65, v4, s1
	v_and_or_b32 v3, v4, s4, v3
	v_mad_u64_u32 v[4:5], s[6:7], v118, 10, v[110:111]
	v_readfirstlane_b32 s0, v1
	v_mul_lo_u32 v4, v4, s5
	s_ashr_i32 s10, s0, 6
	s_mov_b32 s0, 0
	v_add3_u32 v4, 0, v4, v13
	ds_write_b64 v4, v[2:3]
	v_mul_i32_i24_e32 v2, 0x50a0, v77
	s_mov_b32 s1, s0
	v_add3_u32 v2, 0, v2, v13
	v_mov_b64_e32 v[4:5], s[0:1]
	ds_write_b64 v2, v[4:5] offset:18576
	v_mul_i32_i24_e32 v2, 0x50a0, v79
	s_add_i32 s12, s10, s90
	v_add3_u32 v2, 0, v2, v13
	s_cmpk_gt_i32 s12, 0x15f
	ds_write_b64 v2, v[4:5] offset:18576
	s_waitcnt lgkmcnt(0)
	s_barrier
	s_cbranch_scc1 bias_end_l1
	v_and_b32_e32 v4, 15, v1
	v_bfe_u32 v1, v1, 4, 2
	v_lshlrev_b32_e32 v3, 2, v1
	v_min_u32_e32 v2, 9, v4
	v_or_b32_e32 v5, 1, v3
	v_or_b32_e32 v6, 2, v3
	v_or_b32_e32 v3, 3, v3
	v_lshlrev_b32_e32 v74, 2, v4
	v_cmp_gt_u32_e64 s[8:9], 9, v3
	v_mul_u32_u24_e32 v14, 0x810, v2
	v_lshl_add_u64 v[2:3], s[34:35], 0, v[74:75]
	s_mov_b64 s[20:21], 0xbc4c800
	v_cmp_gt_u32_e64 s[6:7], 9, v6
	v_lshl_add_u64 v[6:7], v[2:3], 0, s[20:21]
	s_movk_i32 s3, 0x5800
	v_mov_b32_e32 v2, 0xb000
	v_mad_u32_u24 v10, v5, s3, s3
	v_mad_u32_u24 v12, v5, s3, v2
	v_lshlrev_b32_e32 v2, 4, v1
	s_lshl_b32 s3, s91, 7
	s_lshl_b32 s10, s10, 4
	v_cmp_ne_u32_e64 s[0:1], 3, v1
	v_mul_u32_u24_e32 v74, 0x16000, v1
	v_add3_u32 v1, v14, v2, 0
	v_mov_b32_e32 v3, v75
	s_add_i32 s3, s3, s10
	v_cmp_gt_u32_e64 s[4:5], 9, v5
	v_mul_u32_u24_e32 v8, 0x5800, v5
	v_mov_b32_e32 v9, v75
	v_mov_b32_e32 v11, v75
	v_mov_b32_e32 v13, v75
	v_add_u32_e32 v1, 0xf1e0, v1
	v_lshl_add_u64 v[14:15], s[34:35], 0, v[2:3]
	v_or_b32_e32 v16, s3, v4
	s_lshl_b32 s13, s94, 7
	s_branch .LBB0_1212
.LBB0_1211:
	s_or_b64 exec, exec, s[10:11]
	s_add_i32 s12, s12, s18
	s_cmpk_lt_i32 s12, 0x160
	v_add_u32_e32 v16, s13, v16
	s_cbranch_scc0 bias_end_l1

bias_end_l1:
	s_barrier
	s_mov_b64 s[10:11], s[98:99]
	s_mov_b64 s[20:21], s[100:101]
	s_branch prep_items_l1
